# scan step loop: 2-way hybrid (own half via v_pk_fma_f32 from LDS, partner half via DPP row_ror:8 fused v_fmac), prefetch one step ahead
# speedup vs baseline: 1.0408x; 1.0130x over previous
; __device__ __forceinline__ float red4(float x) { x += dppf(x, 0); x += dppf(x, 1); return x; }
; __device__ __forceinline__ void scan_phase(const Params& p, int j, unsigned char* smem) {
;     ...
; #pragma unroll 2
;             for (int t = 0; t < 16; ++t) {
;                 const float* op = OPS + t * 320 + kq * 16;
;                 f32x4 A4[4], B4[4], W4[4], K4[4], R4[4];
; #pragma unroll
;                 for (int i = 0; i < 4; ++i) A4[i] = *(const f32x4*)(op + i * 4);
; #pragma unroll
;                 for (int i = 0; i < 4; ++i) { W4[i] = *(const f32x4*)(op + 128 + i * 4); B4[i] = *(const f32x4*)(op + 64 + i * 4); K4[i] = *(const f32x4*)(op + 192 + i * 4); }
; #pragma unroll
;                 for (int i = 0; i < 4; ++i) R4[i] = *(const f32x4*)(op + 256 + i * 4);
;                 const float vv = VB[t * 64 + vrow];
;                 f32x2 s0 = {0.f, 0.f}, s1 = {0.f, 0.f};
; #pragma unroll
;                 for (int i = 0; i < 4; ++i) { s0 += S[2 * i] * (f32x2){A4[i][0], A4[i][1]}; s1 += S[2 * i + 1] * (f32x2){A4[i][2], A4[i][3]}; }
;                 const float sa = red4((s0[0] + s0[1]) + (s1[0] + s1[1]));
;                 const f32x2 sa2 = {sa, sa}, vv2 = {vv, vv};
; #pragma unroll
;                 for (int i = 0; i < 4; ++i) {
;                     S[2 * i] = S[2 * i] * (f32x2){W4[i][0], W4[i][1]} + sa2 * (f32x2){B4[i][0], B4[i][1]} + vv2 * (f32x2){K4[i][0], K4[i][1]};
;                     S[2 * i + 1] = S[2 * i + 1] * (f32x2){W4[i][2], W4[i][3]} + sa2 * (f32x2){B4[i][2], B4[i][3]} + vv2 * (f32x2){K4[i][2], K4[i][3]};
;                 }
;                 f32x2 y0 = {0.f, 0.f}, y1 = {0.f, 0.f};
; #pragma unroll
;                 for (int i = 0; i < 4; ++i) { y0 += S[2 * i] * (f32x2){R4[i][0], R4[i][1]}; y1 += S[2 * i + 1] * (f32x2){R4[i][2], R4[i][3]}; }
;                 const float y = red4((y0[0] + y0[1]) + (y1[0] + y1[1]));
;                 if (kq == 0) YB[t * 64 + vrow] = y;
;             }
.LBB0_509:
	v_lshlrev_b32_e32 v66, 2, v226
	v_and_b32_e32 v66, 32, v66
	v_add3_u32 v64, v23, v59, v66
	v_lshl_add_u32 v65, s10, 2, v62
	s_movk_i32 s7, 0xf000
	s_waitcnt lgkmcnt(0)
	s_barrier
	v_add_u32_e32 v66, s7, v65
	ds_read_b128 v[68:71], v64
	ds_read_b128 v[72:75], v64 offset:16
	ds_read_b128 v[76:79], v64 offset:256
	ds_read_b128 v[80:83], v64 offset:272
	ds_read_b128 v[84:87], v64 offset:512
	ds_read_b128 v[88:91], v64 offset:528
	ds_read_b128 v[92:95], v64 offset:768
	ds_read_b128 v[96:99], v64 offset:784
	ds_read_b128 v[100:103], v64 offset:1024
	ds_read_b128 v[104:107], v64 offset:1040
	ds_read_b32 v108, v66 offset:24576
	s_waitcnt lgkmcnt(0)
	ds_read_b128 v[110:113], v64 offset:1280
	ds_read_b128 v[114:117], v64 offset:1296
	ds_read_b128 v[118:121], v64 offset:1536
	ds_read_b128 v[122:125], v64 offset:1552
	ds_read_b128 v[126:129], v64 offset:1792
	ds_read_b128 v[130:133], v64 offset:1808
	ds_read_b128 v[134:137], v64 offset:2048
	ds_read_b128 v[138:141], v64 offset:2064
	ds_read_b128 v[142:145], v64 offset:2304
	ds_read_b128 v[146:149], v64 offset:2320
	ds_read_b32 v150, v66 offset:24832
	s_branch .LBB0_511
.LBB0_510:
	s_addk_i32 s7, 0x200
	s_cmp_eq_u32 s7, 0
	v_add_u32_e32 v64, 0xa00, v64
	s_cbranch_scc1 .LBB0_504
	v_add_u32_e32 v66, s7, v65
.LBB0_511:
	v_pk_mul_f32 v[152:153], v[38:39], v[68:69]
	v_mul_f32_dpp v154, v68, v46 row_ror:8 row_mask:0xf bank_mask:0xf
	v_mul_f32_dpp v155, v69, v47 row_ror:8 row_mask:0xf bank_mask:0xf
	v_pk_fma_f32 v[152:153], v[40:41], v[70:71], v[152:153]
	v_fmac_f32_dpp v154, v70, v48 row_ror:8 row_mask:0xf bank_mask:0xf
	v_fmac_f32_dpp v155, v71, v49 row_ror:8 row_mask:0xf bank_mask:0xf
	v_pk_fma_f32 v[152:153], v[42:43], v[72:73], v[152:153]
	v_fmac_f32_dpp v154, v72, v50 row_ror:8 row_mask:0xf bank_mask:0xf
	v_fmac_f32_dpp v155, v73, v51 row_ror:8 row_mask:0xf bank_mask:0xf
	v_pk_fma_f32 v[152:153], v[44:45], v[74:75], v[152:153]
	v_fmac_f32_dpp v154, v74, v52 row_ror:8 row_mask:0xf bank_mask:0xf
	v_fmac_f32_dpp v155, v75, v53 row_ror:8 row_mask:0xf bank_mask:0xf
	v_add_f32_e32 v154, v154, v155
	v_add_f32_e32 v152, v152, v153
	v_add_f32_e32 v152, v152, v154
	v_pk_mul_f32 v[38:39], v[38:39], v[84:85]
	v_pk_mul_f32 v[40:41], v[40:41], v[86:87]
	v_add_f32_dpp v162, v152, v152 quad_perm:[1,0,3,2] row_mask:0xf bank_mask:0xf bound_ctrl:1
	v_pk_mul_f32 v[42:43], v[42:43], v[88:89]
	v_pk_mul_f32 v[44:45], v[44:45], v[90:91]
	v_add_f32_dpp v156, v162, v162 quad_perm:[2,3,0,1] row_mask:0xf bank_mask:0xf bound_ctrl:1
	v_mul_f32_dpp v46, v84, v46 row_ror:8 row_mask:0xf bank_mask:0xf
	v_mul_f32_dpp v47, v85, v47 row_ror:8 row_mask:0xf bank_mask:0xf
	v_mul_f32_dpp v48, v86, v48 row_ror:8 row_mask:0xf bank_mask:0xf
	v_mul_f32_dpp v49, v87, v49 row_ror:8 row_mask:0xf bank_mask:0xf
	v_mul_f32_dpp v50, v88, v50 row_ror:8 row_mask:0xf bank_mask:0xf
	v_mul_f32_dpp v51, v89, v51 row_ror:8 row_mask:0xf bank_mask:0xf
	v_mul_f32_dpp v52, v90, v52 row_ror:8 row_mask:0xf bank_mask:0xf
	v_mul_f32_dpp v53, v91, v53 row_ror:8 row_mask:0xf bank_mask:0xf
	v_pk_fma_f32 v[38:39], v[76:77], v[156:157], v[38:39] op_sel_hi:[1,0,1]
	v_pk_fma_f32 v[40:41], v[78:79], v[156:157], v[40:41] op_sel_hi:[1,0,1]
	v_pk_fma_f32 v[42:43], v[80:81], v[156:157], v[42:43] op_sel_hi:[1,0,1]
	v_pk_fma_f32 v[44:45], v[82:83], v[156:157], v[44:45] op_sel_hi:[1,0,1]
	v_fmac_f32_dpp v46, v76, v156 row_ror:8 row_mask:0xf bank_mask:0xf
	v_fmac_f32_dpp v47, v77, v156 row_ror:8 row_mask:0xf bank_mask:0xf
	v_fmac_f32_dpp v48, v78, v156 row_ror:8 row_mask:0xf bank_mask:0xf
	v_fmac_f32_dpp v49, v79, v156 row_ror:8 row_mask:0xf bank_mask:0xf
	v_fmac_f32_dpp v50, v80, v156 row_ror:8 row_mask:0xf bank_mask:0xf
	v_fmac_f32_dpp v51, v81, v156 row_ror:8 row_mask:0xf bank_mask:0xf
	v_fmac_f32_dpp v52, v82, v156 row_ror:8 row_mask:0xf bank_mask:0xf
	v_fmac_f32_dpp v53, v83, v156 row_ror:8 row_mask:0xf bank_mask:0xf
	v_pk_fma_f32 v[38:39], v[92:93], v[108:109], v[38:39] op_sel_hi:[1,0,1]
	v_pk_fma_f32 v[40:41], v[94:95], v[108:109], v[40:41] op_sel_hi:[1,0,1]
	v_pk_fma_f32 v[42:43], v[96:97], v[108:109], v[42:43] op_sel_hi:[1,0,1]
	v_pk_fma_f32 v[44:45], v[98:99], v[108:109], v[44:45] op_sel_hi:[1,0,1]
	v_fmac_f32_dpp v46, v92, v108 row_ror:8 row_mask:0xf bank_mask:0xf
	v_fmac_f32_dpp v47, v93, v108 row_ror:8 row_mask:0xf bank_mask:0xf
	v_fmac_f32_dpp v48, v94, v108 row_ror:8 row_mask:0xf bank_mask:0xf
	v_fmac_f32_dpp v49, v95, v108 row_ror:8 row_mask:0xf bank_mask:0xf
	v_fmac_f32_dpp v50, v96, v108 row_ror:8 row_mask:0xf bank_mask:0xf
	v_fmac_f32_dpp v51, v97, v108 row_ror:8 row_mask:0xf bank_mask:0xf
	v_fmac_f32_dpp v52, v98, v108 row_ror:8 row_mask:0xf bank_mask:0xf
	v_fmac_f32_dpp v53, v99, v108 row_ror:8 row_mask:0xf bank_mask:0xf
	v_pk_mul_f32 v[158:159], v[38:39], v[100:101]
	v_mul_f32_dpp v160, v100, v46 row_ror:8 row_mask:0xf bank_mask:0xf
	v_mul_f32_dpp v161, v101, v47 row_ror:8 row_mask:0xf bank_mask:0xf
	v_pk_fma_f32 v[158:159], v[40:41], v[102:103], v[158:159]
	v_fmac_f32_dpp v160, v102, v48 row_ror:8 row_mask:0xf bank_mask:0xf
	v_fmac_f32_dpp v161, v103, v49 row_ror:8 row_mask:0xf bank_mask:0xf
	v_pk_fma_f32 v[158:159], v[42:43], v[104:105], v[158:159]
	v_fmac_f32_dpp v160, v104, v50 row_ror:8 row_mask:0xf bank_mask:0xf
	v_fmac_f32_dpp v161, v105, v51 row_ror:8 row_mask:0xf bank_mask:0xf
	v_pk_fma_f32 v[158:159], v[44:45], v[106:107], v[158:159]
	v_fmac_f32_dpp v160, v106, v52 row_ror:8 row_mask:0xf bank_mask:0xf
	v_fmac_f32_dpp v161, v107, v53 row_ror:8 row_mask:0xf bank_mask:0xf
	v_add_f32_e32 v160, v160, v161
	v_add_f32_e32 v158, v158, v159
	v_add_f32_e32 v158, v158, v160
	s_waitcnt lgkmcnt(0)
; __device__ __forceinline__ float red4(float x) { x += dppf(x, 0); x += dppf(x, 1); return x; }
; __device__ __forceinline__ void scan_phase(const Params& p, int j, unsigned char* smem) {
;     ...
;             for (int t = 0; t < 16; ++t) {
;                 const float* op = OPS + t * 320 + kq * 16;
;                 f32x4 A4[4], B4[4], W4[4], K4[4], R4[4];
; #pragma unroll
;                 for (int i = 0; i < 4; ++i) A4[i] = *(const f32x4*)(op + i * 4);
; #pragma unroll
;                 for (int i = 0; i < 4; ++i) { W4[i] = *(const f32x4*)(op + 128 + i * 4); B4[i] = *(const f32x4*)(op + 64 + i * 4); K4[i] = *(const f32x4*)(op + 192 + i * 4); }
; #pragma unroll
;                 for (int i = 0; i < 4; ++i) R4[i] = *(const f32x4*)(op + 256 + i * 4);
;                 const float vv = VB[t * 64 + vrow];
;                 f32x2 s0 = {0.f, 0.f}, s1 = {0.f, 0.f};
; #pragma unroll
;                 for (int i = 0; i < 4; ++i) { s0 += S[2 * i] * (f32x2){A4[i][0], A4[i][1]}; s1 += S[2 * i + 1] * (f32x2){A4[i][2], A4[i][3]}; }
;                 const float sa = red4((s0[0] + s0[1]) + (s1[0] + s1[1]));
;                 const f32x2 sa2 = {sa, sa}, vv2 = {vv, vv};
; #pragma unroll
;                 for (int i = 0; i < 4; ++i) {
;                     S[2 * i] = S[2 * i] * (f32x2){W4[i][0], W4[i][1]} + sa2 * (f32x2){B4[i][0], B4[i][1]} + vv2 * (f32x2){K4[i][0], K4[i][1]};
;                     S[2 * i + 1] = S[2 * i + 1] * (f32x2){W4[i][2], W4[i][3]} + sa2 * (f32x2){B4[i][2], B4[i][3]} + vv2 * (f32x2){K4[i][2], K4[i][3]};
;                 }
;                 f32x2 y0 = {0.f, 0.f}, y1 = {0.f, 0.f};
; #pragma unroll
;                 for (int i = 0; i < 4; ++i) { y0 += S[2 * i] * (f32x2){R4[i][0], R4[i][1]}; y1 += S[2 * i + 1] * (f32x2){R4[i][2], R4[i][3]}; }
;                 const float y = red4((y0[0] + y0[1]) + (y1[0] + y1[1]));
;                 if (kq == 0) YB[t * 64 + vrow] = y;
;             }
	ds_read_b128 v[68:71], v64 offset:2560
	ds_read_b128 v[72:75], v64 offset:2576
	ds_read_b128 v[76:79], v64 offset:2816
	ds_read_b128 v[80:83], v64 offset:2832
	v_add_f32_dpp v163, v158, v158 quad_perm:[1,0,3,2] row_mask:0xf bank_mask:0xf bound_ctrl:1
	ds_read_b128 v[84:87], v64 offset:3072
	ds_read_b128 v[88:91], v64 offset:3088
	ds_read_b128 v[92:95], v64 offset:3328
	ds_read_b128 v[96:99], v64 offset:3344
	v_add_f32_dpp v160, v163, v163 quad_perm:[2,3,0,1] row_mask:0xf bank_mask:0xf bound_ctrl:1
	ds_read_b128 v[100:103], v64 offset:3584
	ds_read_b128 v[104:107], v64 offset:3600
	ds_read_b32 v108, v66 offset:25088
	s_and_saveexec_b64 s[2:3], s[4:5]
	ds_write_b32 v66, v160 offset:32768
	s_or_b64 exec, exec, s[2:3]
	v_pk_mul_f32 v[152:153], v[38:39], v[110:111]
	v_mul_f32_dpp v154, v110, v46 row_ror:8 row_mask:0xf bank_mask:0xf
	v_mul_f32_dpp v155, v111, v47 row_ror:8 row_mask:0xf bank_mask:0xf
	v_pk_fma_f32 v[152:153], v[40:41], v[112:113], v[152:153]
	v_fmac_f32_dpp v154, v112, v48 row_ror:8 row_mask:0xf bank_mask:0xf
	v_fmac_f32_dpp v155, v113, v49 row_ror:8 row_mask:0xf bank_mask:0xf
	v_pk_fma_f32 v[152:153], v[42:43], v[114:115], v[152:153]
	v_fmac_f32_dpp v154, v114, v50 row_ror:8 row_mask:0xf bank_mask:0xf
	v_fmac_f32_dpp v155, v115, v51 row_ror:8 row_mask:0xf bank_mask:0xf
	v_pk_fma_f32 v[152:153], v[44:45], v[116:117], v[152:153]
	v_fmac_f32_dpp v154, v116, v52 row_ror:8 row_mask:0xf bank_mask:0xf
	v_fmac_f32_dpp v155, v117, v53 row_ror:8 row_mask:0xf bank_mask:0xf
	v_add_f32_e32 v154, v154, v155
	v_add_f32_e32 v152, v152, v153
	v_add_f32_e32 v152, v152, v154
	v_pk_mul_f32 v[38:39], v[38:39], v[126:127]
	v_pk_mul_f32 v[40:41], v[40:41], v[128:129]
	v_add_f32_dpp v162, v152, v152 quad_perm:[1,0,3,2] row_mask:0xf bank_mask:0xf bound_ctrl:1
	v_pk_mul_f32 v[42:43], v[42:43], v[130:131]
	v_pk_mul_f32 v[44:45], v[44:45], v[132:133]
	v_add_f32_dpp v156, v162, v162 quad_perm:[2,3,0,1] row_mask:0xf bank_mask:0xf bound_ctrl:1
	v_mul_f32_dpp v46, v126, v46 row_ror:8 row_mask:0xf bank_mask:0xf
	v_mul_f32_dpp v47, v127, v47 row_ror:8 row_mask:0xf bank_mask:0xf
	v_mul_f32_dpp v48, v128, v48 row_ror:8 row_mask:0xf bank_mask:0xf
	v_mul_f32_dpp v49, v129, v49 row_ror:8 row_mask:0xf bank_mask:0xf
	v_mul_f32_dpp v50, v130, v50 row_ror:8 row_mask:0xf bank_mask:0xf
	v_mul_f32_dpp v51, v131, v51 row_ror:8 row_mask:0xf bank_mask:0xf
	v_mul_f32_dpp v52, v132, v52 row_ror:8 row_mask:0xf bank_mask:0xf
	v_mul_f32_dpp v53, v133, v53 row_ror:8 row_mask:0xf bank_mask:0xf
	v_pk_fma_f32 v[38:39], v[118:119], v[156:157], v[38:39] op_sel_hi:[1,0,1]
	v_pk_fma_f32 v[40:41], v[120:121], v[156:157], v[40:41] op_sel_hi:[1,0,1]
	v_pk_fma_f32 v[42:43], v[122:123], v[156:157], v[42:43] op_sel_hi:[1,0,1]
	v_pk_fma_f32 v[44:45], v[124:125], v[156:157], v[44:45] op_sel_hi:[1,0,1]
	v_fmac_f32_dpp v46, v118, v156 row_ror:8 row_mask:0xf bank_mask:0xf
	v_fmac_f32_dpp v47, v119, v156 row_ror:8 row_mask:0xf bank_mask:0xf
	v_fmac_f32_dpp v48, v120, v156 row_ror:8 row_mask:0xf bank_mask:0xf
	v_fmac_f32_dpp v49, v121, v156 row_ror:8 row_mask:0xf bank_mask:0xf
	v_fmac_f32_dpp v50, v122, v156 row_ror:8 row_mask:0xf bank_mask:0xf
	v_fmac_f32_dpp v51, v123, v156 row_ror:8 row_mask:0xf bank_mask:0xf
	v_fmac_f32_dpp v52, v124, v156 row_ror:8 row_mask:0xf bank_mask:0xf
	v_fmac_f32_dpp v53, v125, v156 row_ror:8 row_mask:0xf bank_mask:0xf
	v_pk_fma_f32 v[38:39], v[134:135], v[150:151], v[38:39] op_sel_hi:[1,0,1]
	v_pk_fma_f32 v[40:41], v[136:137], v[150:151], v[40:41] op_sel_hi:[1,0,1]
	v_pk_fma_f32 v[42:43], v[138:139], v[150:151], v[42:43] op_sel_hi:[1,0,1]
	v_pk_fma_f32 v[44:45], v[140:141], v[150:151], v[44:45] op_sel_hi:[1,0,1]
	v_fmac_f32_dpp v46, v134, v150 row_ror:8 row_mask:0xf bank_mask:0xf
	v_fmac_f32_dpp v47, v135, v150 row_ror:8 row_mask:0xf bank_mask:0xf
	v_fmac_f32_dpp v48, v136, v150 row_ror:8 row_mask:0xf bank_mask:0xf
	v_fmac_f32_dpp v49, v137, v150 row_ror:8 row_mask:0xf bank_mask:0xf
	v_fmac_f32_dpp v50, v138, v150 row_ror:8 row_mask:0xf bank_mask:0xf
	v_fmac_f32_dpp v51, v139, v150 row_ror:8 row_mask:0xf bank_mask:0xf
	v_fmac_f32_dpp v52, v140, v150 row_ror:8 row_mask:0xf bank_mask:0xf
	v_fmac_f32_dpp v53, v141, v150 row_ror:8 row_mask:0xf bank_mask:0xf
	v_pk_mul_f32 v[158:159], v[38:39], v[142:143]
	v_mul_f32_dpp v160, v142, v46 row_ror:8 row_mask:0xf bank_mask:0xf
	v_mul_f32_dpp v161, v143, v47 row_ror:8 row_mask:0xf bank_mask:0xf
	v_pk_fma_f32 v[158:159], v[40:41], v[144:145], v[158:159]
	v_fmac_f32_dpp v160, v144, v48 row_ror:8 row_mask:0xf bank_mask:0xf
	v_fmac_f32_dpp v161, v145, v49 row_ror:8 row_mask:0xf bank_mask:0xf
	v_pk_fma_f32 v[158:159], v[42:43], v[146:147], v[158:159]
	v_fmac_f32_dpp v160, v146, v50 row_ror:8 row_mask:0xf bank_mask:0xf
	v_fmac_f32_dpp v161, v147, v51 row_ror:8 row_mask:0xf bank_mask:0xf
	v_pk_fma_f32 v[158:159], v[44:45], v[148:149], v[158:159]
	v_fmac_f32_dpp v160, v148, v52 row_ror:8 row_mask:0xf bank_mask:0xf
	v_fmac_f32_dpp v161, v149, v53 row_ror:8 row_mask:0xf bank_mask:0xf
	v_add_f32_e32 v160, v160, v161
	v_add_f32_e32 v158, v158, v159
	v_add_f32_e32 v158, v158, v160
	s_waitcnt lgkmcnt(0)
	ds_read_b128 v[110:113], v64 offset:3840
	ds_read_b128 v[114:117], v64 offset:3856
	ds_read_b128 v[118:121], v64 offset:4096
	ds_read_b128 v[122:125], v64 offset:4112
	v_add_f32_dpp v163, v158, v158 quad_perm:[1,0,3,2] row_mask:0xf bank_mask:0xf bound_ctrl:1
	ds_read_b128 v[126:129], v64 offset:4352
	ds_read_b128 v[130:133], v64 offset:4368
	ds_read_b128 v[134:137], v64 offset:4608
	ds_read_b128 v[138:141], v64 offset:4624
	v_add_f32_dpp v160, v163, v163 quad_perm:[2,3,0,1] row_mask:0xf bank_mask:0xf bound_ctrl:1
	ds_read_b128 v[142:145], v64 offset:4864
	ds_read_b128 v[146:149], v64 offset:4880
	ds_read_b32 v150, v66 offset:25344
	s_and_saveexec_b64 s[2:3], s[4:5]
	ds_write_b32 v66, v160 offset:33024
	s_or_b64 exec, exec, s[2:3]
	s_branch .LBB0_510
